# baseline (speedup 1.0000x reference)
; DEVI void partialSM(f32x16& p0, f32x16& p1, float& m_reg, float& mn, float& alpha) {
;     ...
;   float mnC = -mn * C;
; #pragma unroll
;   for (int r = 0; r < 16; ++r) p0[r] = fmaf(p0[r], C, mnC);
; #pragma unroll
;   for (int r = 0; r < 16; ++r) p1[r] = fmaf(p1[r], C, mnC);
; #pragma unroll
;   for (int r = 0; r < 16; ++r) p0[r] = __builtin_amdgcn_exp2f(p0[r]);
.LBB0_989:
	v_cndmask_b32_e64 v222, v89, v222, s[8:9]
	v_mul_f32_e32 v90, 0xbdd53b94, v222
	v_mov_b32_e32 v129, v90
	v_fmamk_f32 v64, v64, 0x3dd53b94, v90
	v_fmamk_f32 v65, v65, 0x3dd53b94, v90
	v_fmamk_f32 v66, v66, 0x3dd53b94, v90
	v_fmamk_f32 v67, v67, 0x3dd53b94, v90
	v_fmamk_f32 v68, v68, 0x3dd53b94, v90
	v_fmamk_f32 v69, v69, 0x3dd53b94, v90
	v_fmamk_f32 v70, v70, 0x3dd53b94, v90
	v_fmamk_f32 v71, v71, 0x3dd53b94, v90
	v_fmamk_f32 v89, v229, 0x3dd53b94, v90
	v_fmamk_f32 v91, v228, 0x3dd53b94, v90
	v_fmamk_f32 v92, v226, 0x3dd53b94, v90
	v_fmamk_f32 v93, v225, 0x3dd53b94, v90
	v_fmamk_f32 v94, v227, 0x3dd53b94, v90
	v_fmamk_f32 v95, v223, 0x3dd53b94, v90
	v_fmamk_f32 v128, v173, 0x3dd53b94, v90
	v_fmac_f32_e32 v129, 0x3dd53b94, v172
	v_exp_f32_e32 v231, v64
	v_exp_f32_e32 v235, v65
	v_exp_f32_e32 v230, v66
	v_exp_f32_e32 v232, v67
	v_exp_f32_e32 v233, v68
	v_exp_f32_e32 v236, v69
	v_exp_f32_e32 v234, v70
	v_exp_f32_e32 v237, v71
	v_exp_f32_e32 v156, v89
	v_exp_f32_e32 v157, v91
	v_exp_f32_e32 v158, v92
	v_exp_f32_e32 v159, v93
	v_exp_f32_e32 v228, v94
	v_exp_f32_e32 v229, v95
	v_exp_f32_e32 v154, v128
	v_exp_f32_e32 v155, v129
	v_add_f32_e32 v64, v204, v221
	v_fmac_f32_e32 v64, v220, v182
	v_add_f32_e32 v182, v170, v171
	v_add_u32_e32 v166, 0x4000, v166
	s_add_i32 s1, s2, 2
	v_fmamk_f32 v80, v80, 0x3dd53b94, v90
	v_fmamk_f32 v81, v81, 0x3dd53b94, v90
	v_fmamk_f32 v152, v82, 0x3dd53b94, v90
	v_fmamk_f32 v153, v83, 0x3dd53b94, v90
	v_fmamk_f32 v150, v84, 0x3dd53b94, v90
	v_fmamk_f32 v151, v85, 0x3dd53b94, v90
	v_fmamk_f32 v148, v86, 0x3dd53b94, v90
	v_fmamk_f32 v149, v87, 0x3dd53b94, v90
	v_fmamk_f32 v142, v78, 0x3dd53b94, v90
	v_fmamk_f32 v143, v79, 0x3dd53b94, v90
	v_fmamk_f32 v146, v76, 0x3dd53b94, v90
	v_fmamk_f32 v147, v77, 0x3dd53b94, v90
	v_fmamk_f32 v140, v74, 0x3dd53b94, v90
	v_fmamk_f32 v141, v75, 0x3dd53b94, v90
	v_fmamk_f32 v144, v72, 0x3dd53b94, v90
	v_fmamk_f32 v145, v73, 0x3dd53b94, v90
	v_fmac_f32_e32 v182, v64, v224
	v_add_u32_e32 v162, s82, v162
	v_add_u32_e32 v164, s82, v164
	s_cmp_ge_u32 s2, s4
	v_add_u32_e32 v168, 0x80000, v168
	s_waitcnt lgkmcnt(0)
	s_barrier
	s_cbranch_scc1 .LBB0_991
	s_mov_b32 s2, s1
	v_mov_b32_e32 v220, v88
	s_branch .LBB0_981
